# SwiGLU GEMM: accumulator zero-init interleaved into the scalar next-unit scheduling code
# baseline (speedup 1.0000x reference)
.LBB0_1073:
	s_ashr_i32 s5, s5, 3
	v_mov_b64_e32 v[2:3], 0
	s_add_i32 s5, s46, s5
	v_mov_b64_e32 v[4:5], 0
	s_abs_i32 s36, s5
	v_mov_b64_e32 v[6:7], 0
	s_mul_hi_u32 s37, s36, s55
	v_mov_b64_e32 v[8:9], 0
	s_mul_i32 s46, s37, s53
	v_mov_b64_e32 v[10:11], 0
	s_ashr_i32 s9, s5, 31
	v_mov_b64_e32 v[12:13], 0
	s_sub_i32 s36, s36, s46
	v_mov_b64_e32 v[14:15], 0
	s_xor_b32 s9, s9, s52
	v_mov_b64_e32 v[16:17], 0
	s_add_i32 s46, s37, 1
	v_mov_b64_e32 v[18:19], 0
	s_sub_i32 s47, s36, s53
	v_mov_b64_e32 v[20:21], 0
	s_cmp_ge_u32 s36, s53
	v_mov_b64_e32 v[22:23], 0
	s_cselect_b32 s37, s46, s37
	v_mov_b64_e32 v[24:25], 0
	s_cselect_b32 s36, s47, s36
	v_mov_b64_e32 v[26:27], 0
	s_add_i32 s46, s37, 1
	v_mov_b64_e32 v[28:29], 0
	s_cmp_ge_u32 s36, s53
	v_mov_b64_e32 v[30:31], 0
	s_cselect_b32 s36, s46, s37
	v_mov_b64_e32 v[32:33], 0
	s_xor_b32 s36, s36, s9
	v_mov_b64_e32 v[34:35], 0
	s_sub_i32 s9, s36, s9
	v_mov_b64_e32 v[36:37], 0
	s_lshl_b32 s36, s9, 3
	v_mov_b64_e32 v[38:39], 0
	s_sub_i32 s37, s73, s36
	v_mov_b64_e32 v[40:41], 0
	s_min_i32 s37, s37, 8
	v_mov_b64_e32 v[42:43], 0
	s_abs_i32 s47, s37
	v_mov_b64_e32 v[44:45], 0
	v_cvt_f32_u32_e32 v0, s47
	s_sub_i32 s48, 0, s47
	v_mov_b64_e32 v[46:47], 0
	s_mul_i32 s9, s9, s51
	v_mov_b64_e32 v[48:49], 0
	s_sub_i32 s5, s5, s9
	v_mov_b64_e32 v[50:51], 0
	v_rcp_iflag_f32_e32 v0, v0
	s_abs_i32 s46, s5
	v_mov_b64_e32 v[52:53], 0
	s_xor_b32 s9, s5, s37
	v_mov_b64_e32 v[54:55], 0
	s_ashr_i32 s9, s9, 31
	v_mov_b64_e32 v[56:57], 0
	v_mul_f32_e32 v0, 0x4f7ffffe, v0
	v_cvt_u32_f32_e32 v0, v0
	s_nop 0
	v_mov_b64_e32 v[58:59], 0
	v_readfirstlane_b32 s49, v0
	s_mul_i32 s48, s48, s49
	v_mov_b64_e32 v[60:61], 0
	s_mul_hi_u32 s48, s49, s48
	v_mov_b64_e32 v[62:63], 0
	s_add_i32 s49, s49, s48
	v_mov_b64_e32 v[64:65], 0
	s_mul_hi_u32 s48, s46, s49
	v_mov_b64_e32 v[66:67], 0
	s_mul_i32 s49, s48, s47
	v_mov_b64_e32 v[68:69], 0
	s_sub_i32 s46, s46, s49
	v_mov_b64_e32 v[70:71], 0
	s_add_i32 s49, s48, 1
	v_mov_b64_e32 v[72:73], 0
	s_sub_i32 s54, s46, s47
	v_mov_b64_e32 v[74:75], 0
	s_cmp_ge_u32 s46, s47
	v_mov_b64_e32 v[76:77], 0
	s_cselect_b32 s48, s49, s48
	v_mov_b64_e32 v[78:79], 0
	s_cselect_b32 s46, s54, s46
	v_mov_b64_e32 v[80:81], 0
	s_add_i32 s49, s48, 1
	v_mov_b64_e32 v[82:83], 0
	s_cmp_ge_u32 s46, s47
	v_mov_b64_e32 v[84:85], 0
	s_cselect_b32 s46, s49, s48
	v_mov_b64_e32 v[86:87], 0
	s_xor_b32 s46, s46, s9
	v_mov_b64_e32 v[88:89], 0
	s_sub_i32 s90, s46, s9
	v_mov_b64_e32 v[90:91], 0
	s_mul_i32 s9, s90, s37
	v_mov_b64_e32 v[92:93], 0
	s_sub_i32 s5, s5, s9
	v_mov_b64_e32 v[94:95], 0
	s_add_i32 s91, s5, s36
	v_mov_b64_e32 v[96:97], 0
	s_mov_b64 s[46:47], -1
	v_mov_b64_e32 v[98:99], 0
	s_and_b64 vcc, exec, s[28:29]
	v_mov_b64_e32 v[100:101], 0
	s_cbranch_vccz .LBB0_1077
	v_readlane_b32 s5, v249, 18
	s_mul_hi_i32 s37, s91, s5
	s_mul_i32 s36, s91, s5
	s_cbranch_execz .LBB0_1078

.LBB0_1081:
	v_mov_b64_e32 v[102:103], 0
	v_mov_b64_e32 v[104:105], 0
	v_mov_b64_e32 v[106:107], 0
	v_mov_b64_e32 v[108:109], 0
	v_mov_b64_e32 v[110:111], 0
	v_mov_b64_e32 v[112:113], 0
	v_mov_b64_e32 v[114:115], 0
	v_mov_b64_e32 v[116:117], 0
	v_mov_b64_e32 v[118:119], 0
	v_mov_b64_e32 v[120:121], 0
	v_mov_b64_e32 v[122:123], 0
	v_mov_b64_e32 v[124:125], 0
	v_mov_b64_e32 v[126:127], 0
	v_mov_b64_e32 v[0:1], 0
	s_mul_i32 s9, s4, s76
	s_mul_hi_i32 s5, s4, s76
	s_add_u32 s9, s18, s9
	s_addc_u32 s5, s19, s5
	s_add_u32 s46, s9, s36
	s_addc_u32 s47, s5, s37
	s_mul_hi_i32 s5, s4, s75
	s_mul_i32 s4, s4, s75
	s_add_u32 s4, s16, s4
	s_addc_u32 s5, s17, s5
	s_add_u32 s48, s4, s48
	s_addc_u32 s49, s5, s49
	s_andn2_b64 vcc, exec, s[34:35]
	s_cbranch_vccnz .LBB0_1083
	s_cmp_lt_i32 s91, 64
	s_cselect_b32 s4, 1, 2
	s_cmp_gt_i32 s91, 31
	s_cselect_b32 s4, s4, 0
	v_readlane_b32 s9, v249, 26
	s_mul_hi_i32 s5, s4, s9
	s_mul_i32 s4, s4, s9
	s_add_u32 s48, s48, s4
	s_addc_u32 s49, s49, s5
	s_branch .LBB0_1083
.Lswz_full:
	v_mov_b64_e32 v[0:1], 0
	v_mov_b64_e32 v[2:3], 0
	v_mov_b64_e32 v[4:5], 0
	v_mov_b64_e32 v[6:7], 0
	v_mov_b64_e32 v[8:9], 0
	v_mov_b64_e32 v[10:11], 0
	v_mov_b64_e32 v[12:13], 0
	v_mov_b64_e32 v[14:15], 0
	v_mov_b64_e32 v[16:17], 0
	v_mov_b64_e32 v[18:19], 0
	v_mov_b64_e32 v[20:21], 0
	v_mov_b64_e32 v[22:23], 0
	v_mov_b64_e32 v[24:25], 0
	v_mov_b64_e32 v[26:27], 0
	v_mov_b64_e32 v[28:29], 0
	v_mov_b64_e32 v[30:31], 0
	v_mov_b64_e32 v[32:33], 0
	v_mov_b64_e32 v[34:35], 0
	v_mov_b64_e32 v[36:37], 0
	v_mov_b64_e32 v[38:39], 0
	v_mov_b64_e32 v[40:41], 0
	v_mov_b64_e32 v[42:43], 0
	v_mov_b64_e32 v[44:45], 0
	v_mov_b64_e32 v[46:47], 0
	v_mov_b64_e32 v[48:49], 0
	v_mov_b64_e32 v[50:51], 0
	v_mov_b64_e32 v[52:53], 0
	v_mov_b64_e32 v[54:55], 0
	v_mov_b64_e32 v[56:57], 0
	v_mov_b64_e32 v[58:59], 0
	v_mov_b64_e32 v[60:61], 0
	v_mov_b64_e32 v[62:63], 0
	v_mov_b64_e32 v[64:65], 0
	v_mov_b64_e32 v[66:67], 0
	v_mov_b64_e32 v[68:69], 0
	v_mov_b64_e32 v[70:71], 0
	v_mov_b64_e32 v[72:73], 0
	v_mov_b64_e32 v[74:75], 0
	v_mov_b64_e32 v[76:77], 0
	v_mov_b64_e32 v[78:79], 0
	v_mov_b64_e32 v[80:81], 0
	v_mov_b64_e32 v[82:83], 0
	v_mov_b64_e32 v[84:85], 0
	v_mov_b64_e32 v[86:87], 0
	v_mov_b64_e32 v[88:89], 0
	v_mov_b64_e32 v[90:91], 0
	v_mov_b64_e32 v[92:93], 0
	v_mov_b64_e32 v[94:95], 0
	v_mov_b64_e32 v[96:97], 0
	v_mov_b64_e32 v[98:99], 0
	v_mov_b64_e32 v[100:101], 0
	v_mov_b64_e32 v[102:103], 0
	v_mov_b64_e32 v[104:105], 0
	v_mov_b64_e32 v[106:107], 0
	v_mov_b64_e32 v[108:109], 0
	v_mov_b64_e32 v[110:111], 0
	v_mov_b64_e32 v[112:113], 0
	v_mov_b64_e32 v[114:115], 0
	v_mov_b64_e32 v[116:117], 0
	v_mov_b64_e32 v[118:119], 0
	v_mov_b64_e32 v[120:121], 0
	v_mov_b64_e32 v[122:123], 0
	v_mov_b64_e32 v[124:125], 0
	v_mov_b64_e32 v[126:127], 0
